# mlstm_pre: 16 row-sum xor butterflies (5 ds_bpermute round trips each) replaced by DPP adds
# speedup vs baseline: 1.0146x; 1.0020x over previous
; DI bf16_t f2bf(float f) { return (bf16_t)(pk2(f, 0.f) & 0xffffu); }
; DI int fragoff(int row, int k, int KS) { return (((row >> 4) * KS + (k >> 5)) << 9) + (((((k >> 3) & 3) << 4) + (row & 15)) << 3) + (k & 7); }
; DI int crow32(int r, int half) { return (r & 3) + 8 * (r >> 2) + 4 * half; }
; DI void mlstm_pre(const Params& p, int ch, char* smem) {
;     ...
;     for (int r = 0; r < 16; ++r) {
;       const int i = ti * 32 + crow32(r, lane >> 5);
;       float pv = (i >= j) ? acc[r] * __expf(s_bc[i] + cj - s_mt[i]) : 0.f;
;       o_p[fragoff(i, j, 2)] = f2bf(pv);
;       pv += __shfl_xor(pv, 1);
;       pv += __shfl_xor(pv, 2);
;       pv += __shfl_xor(pv, 4);
;       pv += __shfl_xor(pv, 8);
;       pv += __shfl_xor(pv, 16);
;       if ((lane & 31) == 0) atomicAdd(&s_rs[i], pv);
;     }
.LBB0_406:
	s_or_b64 exec, exec, s[10:11]
	s_nop 8
	v_cmp_eq_u32_e64 s[8:9], 16, v21
	v_cvt_pk_bf16_f32 v28, v24, s0
	s_add_u32 s12, s60, 0xc000
	s_addc_u32 s13, s61, 0
	s_nop 1
	v_add_f32_dpp v26, v24, v24 quad_perm:[1,0,3,2] row_mask:0xf bank_mask:0xf
	v_lshlrev_b32_e32 v0, 1, v21
	v_lshrrev_b32_e32 v24, 3, v79
	v_and_b32_e32 v25, 48, v0
	v_and_b32_e32 v0, 7, v30
	s_nop 1
	v_add_f32_dpp v21, v26, v26 quad_perm:[2,3,0,1] row_mask:0xf bank_mask:0xf
	s_nop 1
	v_add_f32_dpp v27, v21, v21 row_half_mirror row_mask:0xf bank_mask:0xf
	v_and_or_b32 v21, v24, s76, v16
	v_lshlrev_b32_e32 v26, 9, v21
	v_or_b32_e32 v21, v25, v23
	v_lshlrev_b32_e32 v21, 3, v21
	s_nop 1
	v_add_f32_dpp v24, v27, v27 row_mirror row_mask:0xf bank_mask:0xf
	s_nop 1
	v_add_f32_dpp v27, v24, v24 row_bcast:15 row_mask:0xa bank_mask:0xf
	v_or3_b32 v32, v26, v0, v21
	v_ashrrev_i32_e32 v33, 31, v32
	v_lshl_add_u64 v[32:33], v[32:33], 1, s[12:13]
	global_store_short v[32:33], v28, off
	s_and_saveexec_b64 s[10:11], s[8:9]
	s_cbranch_execz .LBB0_408
	v_mov_b32_e32 v24, v27
	ds_add_f32 v18, v24 offset:36608

; DI bf16_t f2bf(float f) { return (bf16_t)(pk2(f, 0.f) & 0xffffu); }
; DI int fragoff(int row, int k, int KS) { return (((row >> 4) * KS + (k >> 5)) << 9) + (((((k >> 3) & 3) << 4) + (row & 15)) << 3) + (k & 7); }
; DI int crow32(int r, int half) { return (r & 3) + 8 * (r >> 2) + 4 * half; }
; DI void mlstm_pre(const Params& p, int ch, char* smem) {
;     ...
;     for (int r = 0; r < 16; ++r) {
;       const int i = ti * 32 + crow32(r, lane >> 5);
;       float pv = (i >= j) ? acc[r] * __expf(s_bc[i] + cj - s_mt[i]) : 0.f;
;       o_p[fragoff(i, j, 2)] = f2bf(pv);
;       pv += __shfl_xor(pv, 1);
;       pv += __shfl_xor(pv, 2);
;       pv += __shfl_xor(pv, 4);
;       pv += __shfl_xor(pv, 8);
;       pv += __shfl_xor(pv, 16);
;       if ((lane & 31) == 0) atomicAdd(&s_rs[i], pv);
;     }
.LBB0_410:
	s_or_b64 exec, exec, s[14:15]
	v_cvt_pk_bf16_f32 v34, v28, s0
	v_or_b32_e32 v24, v24, v25
	v_lshlrev_b32_e32 v24, 3, v24
	s_nop 1
	v_add_f32_dpp v1, v28, v28 quad_perm:[1,0,3,2] row_mask:0xf bank_mask:0xf
	s_nop 1
	v_add_f32_dpp v1, v1, v1 quad_perm:[2,3,0,1] row_mask:0xf bank_mask:0xf
	s_nop 1
	v_add_f32_dpp v1, v1, v1 row_half_mirror row_mask:0xf bank_mask:0xf
	s_nop 1
	v_add_f32_dpp v1, v1, v1 row_mirror row_mask:0xf bank_mask:0xf
	s_nop 1
	v_add_f32_dpp v28, v1, v1 row_bcast:15 row_mask:0xa bank_mask:0xf
	v_or3_b32 v32, v24, v0, v26
	v_ashrrev_i32_e32 v33, 31, v32
	v_lshl_add_u64 v[32:33], v[32:33], 1, s[12:13]
	global_store_short v[32:33], v34, off
	s_and_saveexec_b64 s[10:11], s[8:9]
	s_cbranch_execz .LBB0_412
	v_mov_b32_e32 v1, v28
	ds_add_f32 v27, v1 offset:36612

; DI bf16_t f2bf(float f) { return (bf16_t)(pk2(f, 0.f) & 0xffffu); }
; DI int fragoff(int row, int k, int KS) { return (((row >> 4) * KS + (k >> 5)) << 9) + (((((k >> 3) & 3) << 4) + (row & 15)) << 3) + (k & 7); }
; DI int crow32(int r, int half) { return (r & 3) + 8 * (r >> 2) + 4 * half; }
; DI void mlstm_pre(const Params& p, int ch, char* smem) {
;     ...
;     for (int r = 0; r < 16; ++r) {
;       const int i = ti * 32 + crow32(r, lane >> 5);
;       float pv = (i >= j) ? acc[r] * __expf(s_bc[i] + cj - s_mt[i]) : 0.f;
;       o_p[fragoff(i, j, 2)] = f2bf(pv);
;       pv += __shfl_xor(pv, 1);
;       pv += __shfl_xor(pv, 2);
;       pv += __shfl_xor(pv, 4);
;       pv += __shfl_xor(pv, 8);
;       pv += __shfl_xor(pv, 16);
;       if ((lane & 31) == 0) atomicAdd(&s_rs[i], pv);
;     }
.LBB0_414:
	s_or_b64 exec, exec, s[14:15]
	v_or_b32_e32 v1, v1, v25
	v_cvt_pk_bf16_f32 v34, v28, s0
	s_nop 1
	v_add_f32_dpp v2, v28, v28 quad_perm:[1,0,3,2] row_mask:0xf bank_mask:0xf
	s_nop 1
	v_add_f32_dpp v2, v2, v2 quad_perm:[2,3,0,1] row_mask:0xf bank_mask:0xf
	s_nop 1
	v_add_f32_dpp v32, v2, v2 row_half_mirror row_mask:0xf bank_mask:0xf
	v_lshlrev_b32_e32 v2, 3, v1
	s_nop 1
	v_add_f32_dpp v1, v32, v32 row_mirror row_mask:0xf bank_mask:0xf
	s_nop 1
	v_add_f32_dpp v28, v1, v1 row_bcast:15 row_mask:0xa bank_mask:0xf
	v_or3_b32 v32, v2, v0, v26
	v_ashrrev_i32_e32 v33, 31, v32
	v_lshl_add_u64 v[32:33], v[32:33], 1, s[12:13]
	global_store_short v[32:33], v34, off
	s_and_saveexec_b64 s[10:11], s[8:9]
	s_cbranch_execz .LBB0_416
	v_mov_b32_e32 v1, v28
	ds_add_f32 v27, v1 offset:36616

; DI bf16_t f2bf(float f) { return (bf16_t)(pk2(f, 0.f) & 0xffffu); }
; DI int fragoff(int row, int k, int KS) { return (((row >> 4) * KS + (k >> 5)) << 9) + (((((k >> 3) & 3) << 4) + (row & 15)) << 3) + (k & 7); }
; DI int crow32(int r, int half) { return (r & 3) + 8 * (r >> 2) + 4 * half; }
; DI void mlstm_pre(const Params& p, int ch, char* smem) {
;     ...
;     for (int r = 0; r < 16; ++r) {
;       const int i = ti * 32 + crow32(r, lane >> 5);
;       float pv = (i >= j) ? acc[r] * __expf(s_bc[i] + cj - s_mt[i]) : 0.f;
;       o_p[fragoff(i, j, 2)] = f2bf(pv);
;       pv += __shfl_xor(pv, 1);
;       pv += __shfl_xor(pv, 2);
;       pv += __shfl_xor(pv, 4);
;       pv += __shfl_xor(pv, 8);
;       pv += __shfl_xor(pv, 16);
;       if ((lane & 31) == 0) atomicAdd(&s_rs[i], pv);
;     }
.LBB0_418:
	s_or_b64 exec, exec, s[14:15]
	v_cvt_pk_bf16_f32 v34, v28, s0
	v_or_b32_e32 v1, v1, v25
	v_lshlrev_b32_e32 v1, 3, v1
	s_nop 1
	v_add_f32_dpp v3, v28, v28 quad_perm:[1,0,3,2] row_mask:0xf bank_mask:0xf
	s_nop 1
	v_add_f32_dpp v3, v3, v3 quad_perm:[2,3,0,1] row_mask:0xf bank_mask:0xf
	s_nop 1
	v_add_f32_dpp v3, v3, v3 row_half_mirror row_mask:0xf bank_mask:0xf
	s_nop 1
	v_add_f32_dpp v3, v3, v3 row_mirror row_mask:0xf bank_mask:0xf
	s_nop 1
	v_add_f32_dpp v28, v3, v3 row_bcast:15 row_mask:0xa bank_mask:0xf
	v_or3_b32 v32, v1, v0, v26
	v_ashrrev_i32_e32 v33, 31, v32
	v_lshl_add_u64 v[32:33], v[32:33], 1, s[12:13]
	global_store_short v[32:33], v34, off
	s_and_saveexec_b64 s[10:11], s[8:9]
	s_cbranch_execz .LBB0_420
	v_mov_b32_e32 v3, v28
	ds_add_f32 v27, v3 offset:36620

; DI bf16_t f2bf(float f) { return (bf16_t)(pk2(f, 0.f) & 0xffffu); }
; DI int fragoff(int row, int k, int KS) { return (((row >> 4) * KS + (k >> 5)) << 9) + (((((k >> 3) & 3) << 4) + (row & 15)) << 3) + (k & 7); }
; DI int crow32(int r, int half) { return (r & 3) + 8 * (r >> 2) + 4 * half; }
; DI void mlstm_pre(const Params& p, int ch, char* smem) {
;     ...
;     for (int r = 0; r < 16; ++r) {
;       const int i = ti * 32 + crow32(r, lane >> 5);
;       float pv = (i >= j) ? acc[r] * __expf(s_bc[i] + cj - s_mt[i]) : 0.f;
;       o_p[fragoff(i, j, 2)] = f2bf(pv);
;       pv += __shfl_xor(pv, 1);
;       pv += __shfl_xor(pv, 2);
;       pv += __shfl_xor(pv, 4);
;       pv += __shfl_xor(pv, 8);
;       pv += __shfl_xor(pv, 16);
;       if ((lane & 31) == 0) atomicAdd(&s_rs[i], pv);
;     }
.LBB0_422:
	s_or_b64 exec, exec, s[14:15]
	v_or_b32_e32 v3, v3, v25
	v_lshlrev_b32_e32 v33, 3, v3
	s_nop 1
	v_add_f32_dpp v4, v28, v28 quad_perm:[1,0,3,2] row_mask:0xf bank_mask:0xf
	v_cvt_pk_bf16_f32 v28, v28, s0
	s_nop 1
	v_add_f32_dpp v4, v4, v4 quad_perm:[2,3,0,1] row_mask:0xf bank_mask:0xf
	s_nop 1
	v_add_f32_dpp v4, v4, v4 row_half_mirror row_mask:0xf bank_mask:0xf
	s_nop 1
	v_add_f32_dpp v3, v4, v4 row_mirror row_mask:0xf bank_mask:0xf
	s_nop 1
	v_add_f32_dpp v4, v3, v3 row_bcast:15 row_mask:0xa bank_mask:0xf
	v_or3_b32 v32, v26, v33, v0
	v_ashrrev_i32_e32 v33, 31, v32
	v_lshl_add_u64 v[32:33], v[32:33], 1, s[12:13]
	global_store_short v[32:33], v28, off
	s_and_saveexec_b64 s[10:11], s[8:9]
	s_cbranch_execz .LBB0_424
	v_mov_b32_e32 v3, v4
	ds_add_f32 v27, v3 offset:36640

; DI bf16_t f2bf(float f) { return (bf16_t)(pk2(f, 0.f) & 0xffffu); }
; DI int fragoff(int row, int k, int KS) { return (((row >> 4) * KS + (k >> 5)) << 9) + (((((k >> 3) & 3) << 4) + (row & 15)) << 3) + (k & 7); }
; DI int crow32(int r, int half) { return (r & 3) + 8 * (r >> 2) + 4 * half; }
; DI void mlstm_pre(const Params& p, int ch, char* smem) {
;     ...
;     for (int r = 0; r < 16; ++r) {
;       const int i = ti * 32 + crow32(r, lane >> 5);
;       float pv = (i >= j) ? acc[r] * __expf(s_bc[i] + cj - s_mt[i]) : 0.f;
;       o_p[fragoff(i, j, 2)] = f2bf(pv);
;       pv += __shfl_xor(pv, 1);
;       pv += __shfl_xor(pv, 2);
;       pv += __shfl_xor(pv, 4);
;       pv += __shfl_xor(pv, 8);
;       pv += __shfl_xor(pv, 16);
;       if ((lane & 31) == 0) atomicAdd(&s_rs[i], pv);
;     }
.LBB0_426:
	s_or_b64 exec, exec, s[14:15]
	v_or_b32_e32 v3, v3, v25
	v_lshlrev_b32_e32 v32, 3, v3
	v_cvt_pk_bf16_f32 v34, v4, s0
	v_or3_b32 v32, v26, v32, v0
	s_nop 1
	v_add_f32_dpp v5, v4, v4 quad_perm:[1,0,3,2] row_mask:0xf bank_mask:0xf
	v_ashrrev_i32_e32 v33, 31, v32
	v_lshl_add_u64 v[32:33], v[32:33], 1, s[12:13]
	global_store_short v[32:33], v34, off
	s_nop 1
	v_add_f32_dpp v5, v5, v5 quad_perm:[2,3,0,1] row_mask:0xf bank_mask:0xf
	s_nop 1
	v_add_f32_dpp v5, v5, v5 row_half_mirror row_mask:0xf bank_mask:0xf
	s_nop 1
	v_add_f32_dpp v3, v5, v5 row_mirror row_mask:0xf bank_mask:0xf
	s_nop 1
	v_add_f32_dpp v4, v3, v3 row_bcast:15 row_mask:0xa bank_mask:0xf
	s_and_saveexec_b64 s[10:11], s[8:9]
	s_cbranch_execz .LBB0_428
	v_mov_b32_e32 v3, v4
	ds_add_f32 v27, v3 offset:36644

; DI bf16_t f2bf(float f) { return (bf16_t)(pk2(f, 0.f) & 0xffffu); }
; DI int fragoff(int row, int k, int KS) { return (((row >> 4) * KS + (k >> 5)) << 9) + (((((k >> 3) & 3) << 4) + (row & 15)) << 3) + (k & 7); }
; DI int crow32(int r, int half) { return (r & 3) + 8 * (r >> 2) + 4 * half; }
; DI void mlstm_pre(const Params& p, int ch, char* smem) {
;     ...
;     for (int r = 0; r < 16; ++r) {
;       const int i = ti * 32 + crow32(r, lane >> 5);
;       float pv = (i >= j) ? acc[r] * __expf(s_bc[i] + cj - s_mt[i]) : 0.f;
;       o_p[fragoff(i, j, 2)] = f2bf(pv);
;       pv += __shfl_xor(pv, 1);
;       pv += __shfl_xor(pv, 2);
;       pv += __shfl_xor(pv, 4);
;       pv += __shfl_xor(pv, 8);
;       pv += __shfl_xor(pv, 16);
;       if ((lane & 31) == 0) atomicAdd(&s_rs[i], pv);
;     }
.LBB0_430:
	s_or_b64 exec, exec, s[14:15]
	v_or_b32_e32 v3, v3, v25
	v_lshlrev_b32_e32 v32, 3, v3
	v_cvt_pk_bf16_f32 v28, v4, s0
	v_or3_b32 v32, v26, v32, v0
	s_nop 1
	v_add_f32_dpp v5, v4, v4 quad_perm:[1,0,3,2] row_mask:0xf bank_mask:0xf
	v_ashrrev_i32_e32 v33, 31, v32
	v_lshl_add_u64 v[32:33], v[32:33], 1, s[12:13]
	global_store_short v[32:33], v28, off
	s_nop 1
	v_add_f32_dpp v5, v5, v5 quad_perm:[2,3,0,1] row_mask:0xf bank_mask:0xf
	s_nop 1
	v_add_f32_dpp v5, v5, v5 row_half_mirror row_mask:0xf bank_mask:0xf
	s_nop 1
	v_add_f32_dpp v3, v5, v5 row_mirror row_mask:0xf bank_mask:0xf
	s_nop 1
	v_add_f32_dpp v4, v3, v3 row_bcast:15 row_mask:0xa bank_mask:0xf
	s_and_saveexec_b64 s[10:11], s[8:9]
	s_cbranch_execz .LBB0_432
	v_mov_b32_e32 v3, v4
	ds_add_f32 v27, v3 offset:36648

; DI bf16_t f2bf(float f) { return (bf16_t)(pk2(f, 0.f) & 0xffffu); }
; DI int fragoff(int row, int k, int KS) { return (((row >> 4) * KS + (k >> 5)) << 9) + (((((k >> 3) & 3) << 4) + (row & 15)) << 3) + (k & 7); }
; DI int crow32(int r, int half) { return (r & 3) + 8 * (r >> 2) + 4 * half; }
; DI void mlstm_pre(const Params& p, int ch, char* smem) {
;     ...
;     for (int r = 0; r < 16; ++r) {
;       const int i = ti * 32 + crow32(r, lane >> 5);
;       float pv = (i >= j) ? acc[r] * __expf(s_bc[i] + cj - s_mt[i]) : 0.f;
;       o_p[fragoff(i, j, 2)] = f2bf(pv);
;       pv += __shfl_xor(pv, 1);
;       pv += __shfl_xor(pv, 2);
;       pv += __shfl_xor(pv, 4);
;       pv += __shfl_xor(pv, 8);
;       pv += __shfl_xor(pv, 16);
;       if ((lane & 31) == 0) atomicAdd(&s_rs[i], pv);
;     }
.LBB0_434:
	s_or_b64 exec, exec, s[14:15]
	v_or_b32_e32 v3, v3, v25
	v_lshlrev_b32_e32 v7, 3, v3
	v_cvt_pk_bf16_f32 v22, v4, s0
	s_nop 1
	v_add_f32_dpp v5, v4, v4 quad_perm:[1,0,3,2] row_mask:0xf bank_mask:0xf
	s_nop 1
	v_add_f32_dpp v5, v5, v5 quad_perm:[2,3,0,1] row_mask:0xf bank_mask:0xf
	s_nop 1
	v_add_f32_dpp v5, v5, v5 row_half_mirror row_mask:0xf bank_mask:0xf
	s_nop 1
	v_add_f32_dpp v3, v5, v5 row_mirror row_mask:0xf bank_mask:0xf
	s_nop 1
	v_add_f32_dpp v4, v3, v3 row_bcast:15 row_mask:0xa bank_mask:0xf
	v_or3_b32 v6, v26, v7, v0
	v_ashrrev_i32_e32 v7, 31, v6
	v_lshl_add_u64 v[6:7], v[6:7], 1, s[12:13]
	global_store_short v[6:7], v22, off
	s_and_saveexec_b64 s[10:11], s[8:9]
	s_cbranch_execz .LBB0_436
	v_mov_b32_e32 v3, v4
	ds_add_f32 v27, v3 offset:36652

; DI bf16_t f2bf(float f) { return (bf16_t)(pk2(f, 0.f) & 0xffffu); }
; DI int fragoff(int row, int k, int KS) { return (((row >> 4) * KS + (k >> 5)) << 9) + (((((k >> 3) & 3) << 4) + (row & 15)) << 3) + (k & 7); }
; DI int crow32(int r, int half) { return (r & 3) + 8 * (r >> 2) + 4 * half; }
; DI void mlstm_pre(const Params& p, int ch, char* smem) {
;     ...
;     for (int r = 0; r < 16; ++r) {
;       const int i = ti * 32 + crow32(r, lane >> 5);
;       float pv = (i >= j) ? acc[r] * __expf(s_bc[i] + cj - s_mt[i]) : 0.f;
;       o_p[fragoff(i, j, 2)] = f2bf(pv);
;       pv += __shfl_xor(pv, 1);
;       pv += __shfl_xor(pv, 2);
;       pv += __shfl_xor(pv, 4);
;       pv += __shfl_xor(pv, 8);
;       pv += __shfl_xor(pv, 16);
;       if ((lane & 31) == 0) atomicAdd(&s_rs[i], pv);
;     }
.LBB0_438:
	s_or_b64 exec, exec, s[14:15]
	v_lshrrev_b32_e32 v3, 3, v3
	v_and_or_b32 v3, v3, s80, v16
	v_lshlrev_b32_e32 v7, 9, v3
	v_cvt_pk_bf16_f32 v8, v4, s0
	s_nop 1
	v_add_f32_dpp v5, v4, v4 quad_perm:[1,0,3,2] row_mask:0xf bank_mask:0xf
	s_nop 1
	v_add_f32_dpp v5, v5, v5 quad_perm:[2,3,0,1] row_mask:0xf bank_mask:0xf
	s_nop 1
	v_add_f32_dpp v5, v5, v5 row_half_mirror row_mask:0xf bank_mask:0xf
	s_nop 1
	v_add_f32_dpp v3, v5, v5 row_mirror row_mask:0xf bank_mask:0xf
	s_nop 1
	v_add_f32_dpp v4, v3, v3 row_bcast:15 row_mask:0xa bank_mask:0xf
	v_or3_b32 v6, v7, v21, v0
	v_ashrrev_i32_e32 v7, 31, v6
	v_lshl_add_u64 v[6:7], v[6:7], 1, s[12:13]
	global_store_short v[6:7], v8, off
	s_and_saveexec_b64 s[10:11], s[8:9]
	s_cbranch_execz .LBB0_440
	v_mov_b32_e32 v3, v4
	ds_add_f32 v18, v3 offset:36672

; DI bf16_t f2bf(float f) { return (bf16_t)(pk2(f, 0.f) & 0xffffu); }
; DI int fragoff(int row, int k, int KS) { return (((row >> 4) * KS + (k >> 5)) << 9) + (((((k >> 3) & 3) << 4) + (row & 15)) << 3) + (k & 7); }
; DI int crow32(int r, int half) { return (r & 3) + 8 * (r >> 2) + 4 * half; }
; DI void mlstm_pre(const Params& p, int ch, char* smem) {
;     ...
;     for (int r = 0; r < 16; ++r) {
;       const int i = ti * 32 + crow32(r, lane >> 5);
;       float pv = (i >= j) ? acc[r] * __expf(s_bc[i] + cj - s_mt[i]) : 0.f;
;       o_p[fragoff(i, j, 2)] = f2bf(pv);
;       pv += __shfl_xor(pv, 1);
;       pv += __shfl_xor(pv, 2);
;       pv += __shfl_xor(pv, 4);
;       pv += __shfl_xor(pv, 8);
;       pv += __shfl_xor(pv, 16);
;       if ((lane & 31) == 0) atomicAdd(&s_rs[i], pv);
;     }
.LBB0_442:
	s_or_b64 exec, exec, s[14:15]
	v_lshrrev_b32_e32 v3, 3, v3
	v_and_or_b32 v3, v3, s80, v16
	v_lshlrev_b32_e32 v7, 9, v3
	v_cvt_pk_bf16_f32 v8, v4, s0
	s_nop 1
	v_add_f32_dpp v5, v4, v4 quad_perm:[1,0,3,2] row_mask:0xf bank_mask:0xf
	s_nop 1
	v_add_f32_dpp v5, v5, v5 quad_perm:[2,3,0,1] row_mask:0xf bank_mask:0xf
	s_nop 1
	v_add_f32_dpp v5, v5, v5 row_half_mirror row_mask:0xf bank_mask:0xf
	s_nop 1
	v_add_f32_dpp v3, v5, v5 row_mirror row_mask:0xf bank_mask:0xf
	s_nop 1
	v_add_f32_dpp v4, v3, v3 row_bcast:15 row_mask:0xa bank_mask:0xf
	v_or3_b32 v6, v7, v24, v0
	v_ashrrev_i32_e32 v7, 31, v6
	v_lshl_add_u64 v[6:7], v[6:7], 1, s[12:13]
	global_store_short v[6:7], v8, off
	s_and_saveexec_b64 s[10:11], s[8:9]
	s_cbranch_execz .LBB0_444
	v_mov_b32_e32 v3, v4
	ds_add_f32 v18, v3 offset:36676

; DI bf16_t f2bf(float f) { return (bf16_t)(pk2(f, 0.f) & 0xffffu); }
; DI int fragoff(int row, int k, int KS) { return (((row >> 4) * KS + (k >> 5)) << 9) + (((((k >> 3) & 3) << 4) + (row & 15)) << 3) + (k & 7); }
; DI int crow32(int r, int half) { return (r & 3) + 8 * (r >> 2) + 4 * half; }
; DI void mlstm_pre(const Params& p, int ch, char* smem) {
;     ...
;     for (int r = 0; r < 16; ++r) {
;       const int i = ti * 32 + crow32(r, lane >> 5);
;       float pv = (i >= j) ? acc[r] * __expf(s_bc[i] + cj - s_mt[i]) : 0.f;
;       o_p[fragoff(i, j, 2)] = f2bf(pv);
;       pv += __shfl_xor(pv, 1);
;       pv += __shfl_xor(pv, 2);
;       pv += __shfl_xor(pv, 4);
;       pv += __shfl_xor(pv, 8);
;       pv += __shfl_xor(pv, 16);
;       if ((lane & 31) == 0) atomicAdd(&s_rs[i], pv);
;     }
.LBB0_446:
	s_or_b64 exec, exec, s[14:15]
	v_lshrrev_b32_e32 v3, 3, v3
	v_and_or_b32 v3, v3, s80, v16
	v_lshlrev_b32_e32 v7, 9, v3
	v_cvt_pk_bf16_f32 v8, v4, s0
	s_nop 1
	v_add_f32_dpp v5, v4, v4 quad_perm:[1,0,3,2] row_mask:0xf bank_mask:0xf
	s_nop 1
	v_add_f32_dpp v5, v5, v5 quad_perm:[2,3,0,1] row_mask:0xf bank_mask:0xf
	s_nop 1
	v_add_f32_dpp v5, v5, v5 row_half_mirror row_mask:0xf bank_mask:0xf
	s_nop 1
	v_add_f32_dpp v3, v5, v5 row_mirror row_mask:0xf bank_mask:0xf
	s_nop 1
	v_add_f32_dpp v4, v3, v3 row_bcast:15 row_mask:0xa bank_mask:0xf
	v_or3_b32 v6, v7, v2, v0
	v_ashrrev_i32_e32 v7, 31, v6
	v_lshl_add_u64 v[6:7], v[6:7], 1, s[12:13]
	global_store_short v[6:7], v8, off
	s_and_saveexec_b64 s[10:11], s[8:9]
	s_cbranch_execz .LBB0_448
	v_mov_b32_e32 v2, v4
	ds_add_f32 v18, v2 offset:36680

; DI bf16_t f2bf(float f) { return (bf16_t)(pk2(f, 0.f) & 0xffffu); }
; DI int fragoff(int row, int k, int KS) { return (((row >> 4) * KS + (k >> 5)) << 9) + (((((k >> 3) & 3) << 4) + (row & 15)) << 3) + (k & 7); }
; DI int crow32(int r, int half) { return (r & 3) + 8 * (r >> 2) + 4 * half; }
; DI void mlstm_pre(const Params& p, int ch, char* smem) {
;     ...
;     for (int r = 0; r < 16; ++r) {
;       const int i = ti * 32 + crow32(r, lane >> 5);
;       float pv = (i >= j) ? acc[r] * __expf(s_bc[i] + cj - s_mt[i]) : 0.f;
;       o_p[fragoff(i, j, 2)] = f2bf(pv);
;       pv += __shfl_xor(pv, 1);
;       pv += __shfl_xor(pv, 2);
;       pv += __shfl_xor(pv, 4);
;       pv += __shfl_xor(pv, 8);
;       pv += __shfl_xor(pv, 16);
;       if ((lane & 31) == 0) atomicAdd(&s_rs[i], pv);
;     }
.LBB0_450:
	s_or_b64 exec, exec, s[14:15]
	s_waitcnt lgkmcnt(0)
	v_lshrrev_b32_e32 v2, 3, v2
	v_and_or_b32 v2, v2, s80, v16
	v_lshlrev_b32_e32 v7, 9, v2
	v_cvt_pk_bf16_f32 v6, v3, s0
	s_nop 1
	v_add_f32_dpp v4, v3, v3 quad_perm:[1,0,3,2] row_mask:0xf bank_mask:0xf
	s_nop 1
	v_add_f32_dpp v4, v4, v4 quad_perm:[2,3,0,1] row_mask:0xf bank_mask:0xf
	s_nop 1
	v_add_f32_dpp v4, v4, v4 row_half_mirror row_mask:0xf bank_mask:0xf
	s_nop 1
	v_add_f32_dpp v2, v4, v4 row_mirror row_mask:0xf bank_mask:0xf
	s_nop 1
	v_add_f32_dpp v3, v2, v2 row_bcast:15 row_mask:0xa bank_mask:0xf
	v_or3_b32 v4, v7, v1, v0
	v_ashrrev_i32_e32 v5, 31, v4
	v_lshl_add_u64 v[4:5], v[4:5], 1, s[12:13]
	global_store_short v[4:5], v6, off
	s_and_saveexec_b64 s[10:11], s[8:9]
	s_cbranch_execz .LBB0_452
	v_mov_b32_e32 v1, v3
	ds_add_f32 v18, v1 offset:36684

; DI bf16_t f2bf(float f) { return (bf16_t)(pk2(f, 0.f) & 0xffffu); }
; DI int fragoff(int row, int k, int KS) { return (((row >> 4) * KS + (k >> 5)) << 9) + (((((k >> 3) & 3) << 4) + (row & 15)) << 3) + (k & 7); }
; DI int crow32(int r, int half) { return (r & 3) + 8 * (r >> 2) + 4 * half; }
; DI void mlstm_pre(const Params& p, int ch, char* smem) {
;     ...
;     for (int r = 0; r < 16; ++r) {
;       const int i = ti * 32 + crow32(r, lane >> 5);
;       float pv = (i >= j) ? acc[r] * __expf(s_bc[i] + cj - s_mt[i]) : 0.f;
;       o_p[fragoff(i, j, 2)] = f2bf(pv);
;       pv += __shfl_xor(pv, 1);
;       pv += __shfl_xor(pv, 2);
;       pv += __shfl_xor(pv, 4);
;       pv += __shfl_xor(pv, 8);
;       pv += __shfl_xor(pv, 16);
;       if ((lane & 31) == 0) atomicAdd(&s_rs[i], pv);
;     }
.LBB0_454:
	s_or_b64 exec, exec, s[14:15]
	s_waitcnt lgkmcnt(0)
	v_lshrrev_b32_e32 v1, 3, v1
	v_and_or_b32 v1, v1, s80, v16
	v_lshl_or_b32 v5, v1, 9, v21
	v_cvt_pk_bf16_f32 v6, v2, s0
	s_nop 1
	v_add_f32_dpp v3, v2, v2 quad_perm:[1,0,3,2] row_mask:0xf bank_mask:0xf
	s_nop 1
	v_add_f32_dpp v3, v3, v3 quad_perm:[2,3,0,1] row_mask:0xf bank_mask:0xf
	s_nop 1
	v_add_f32_dpp v3, v3, v3 row_half_mirror row_mask:0xf bank_mask:0xf
	s_nop 1
	v_add_f32_dpp v1, v3, v3 row_mirror row_mask:0xf bank_mask:0xf
	s_nop 1
	v_add_f32_dpp v2, v1, v1 row_bcast:15 row_mask:0xa bank_mask:0xf
	v_or3_b32 v4, v5, v0, 64
	v_ashrrev_i32_e32 v5, 31, v4
	v_lshl_add_u64 v[4:5], v[4:5], 1, s[12:13]
	global_store_short v[4:5], v6, off
	s_and_saveexec_b64 s[10:11], s[8:9]
	s_cbranch_execz .LBB0_456
	v_mov_b32_e32 v1, v2
	ds_add_f32 v18, v1 offset:36704

; DI bf16_t f2bf(float f) { return (bf16_t)(pk2(f, 0.f) & 0xffffu); }
; DI int fragoff(int row, int k, int KS) { return (((row >> 4) * KS + (k >> 5)) << 9) + (((((k >> 3) & 3) << 4) + (row & 15)) << 3) + (k & 7); }
; DI int crow32(int r, int half) { return (r & 3) + 8 * (r >> 2) + 4 * half; }
; DI void mlstm_pre(const Params& p, int ch, char* smem) {
;     ...
;     for (int r = 0; r < 16; ++r) {
;       const int i = ti * 32 + crow32(r, lane >> 5);
;       float pv = (i >= j) ? acc[r] * __expf(s_bc[i] + cj - s_mt[i]) : 0.f;
;       o_p[fragoff(i, j, 2)] = f2bf(pv);
;       pv += __shfl_xor(pv, 1);
;       pv += __shfl_xor(pv, 2);
;       pv += __shfl_xor(pv, 4);
;       pv += __shfl_xor(pv, 8);
;       pv += __shfl_xor(pv, 16);
;       if ((lane & 31) == 0) atomicAdd(&s_rs[i], pv);
;     }
.LBB0_458:
	s_or_b64 exec, exec, s[14:15]
	v_lshrrev_b32_e32 v1, 3, v1
	v_and_or_b32 v1, v1, s80, v16
	v_lshl_or_b32 v5, v1, 9, v21
	v_cvt_pk_bf16_f32 v6, v2, s0
	s_nop 1
	v_add_f32_dpp v3, v2, v2 quad_perm:[1,0,3,2] row_mask:0xf bank_mask:0xf
	s_movk_i32 s10, 0x48
	s_nop 1
	v_add_f32_dpp v3, v3, v3 quad_perm:[2,3,0,1] row_mask:0xf bank_mask:0xf
	s_nop 1
	v_add_f32_dpp v3, v3, v3 row_half_mirror row_mask:0xf bank_mask:0xf
	s_nop 1
	v_add_f32_dpp v1, v3, v3 row_mirror row_mask:0xf bank_mask:0xf
	s_nop 1
	v_add_f32_dpp v2, v1, v1 row_bcast:15 row_mask:0xa bank_mask:0xf
	v_or3_b32 v4, v5, v0, s10
	v_ashrrev_i32_e32 v5, 31, v4
	v_lshl_add_u64 v[4:5], v[4:5], 1, s[12:13]
	global_store_short v[4:5], v6, off
	s_and_saveexec_b64 s[10:11], s[8:9]
	s_cbranch_execz .LBB0_460
	v_mov_b32_e32 v1, v2
	ds_add_f32 v18, v1 offset:36708

; DI bf16_t f2bf(float f) { return (bf16_t)(pk2(f, 0.f) & 0xffffu); }
; DI int fragoff(int row, int k, int KS) { return (((row >> 4) * KS + (k >> 5)) << 9) + (((((k >> 3) & 3) << 4) + (row & 15)) << 3) + (k & 7); }
; DI int crow32(int r, int half) { return (r & 3) + 8 * (r >> 2) + 4 * half; }
; DI void mlstm_pre(const Params& p, int ch, char* smem) {
;     ...
;     for (int r = 0; r < 16; ++r) {
;       const int i = ti * 32 + crow32(r, lane >> 5);
;       float pv = (i >= j) ? acc[r] * __expf(s_bc[i] + cj - s_mt[i]) : 0.f;
;       o_p[fragoff(i, j, 2)] = f2bf(pv);
;       pv += __shfl_xor(pv, 1);
;       pv += __shfl_xor(pv, 2);
;       pv += __shfl_xor(pv, 4);
;       pv += __shfl_xor(pv, 8);
;       pv += __shfl_xor(pv, 16);
;       if ((lane & 31) == 0) atomicAdd(&s_rs[i], pv);
;     }
.LBB0_462:
	s_or_b64 exec, exec, s[14:15]
	v_lshrrev_b32_e32 v1, 3, v1
	v_and_or_b32 v1, v1, s80, v16
	v_lshl_or_b32 v5, v1, 9, v21
	v_cvt_pk_bf16_f32 v6, v2, s0
	s_nop 1
	v_add_f32_dpp v3, v2, v2 quad_perm:[1,0,3,2] row_mask:0xf bank_mask:0xf
	s_nop 1
	v_add_f32_dpp v3, v3, v3 quad_perm:[2,3,0,1] row_mask:0xf bank_mask:0xf
	s_nop 1
	v_add_f32_dpp v3, v3, v3 row_half_mirror row_mask:0xf bank_mask:0xf
	s_nop 1
	v_add_f32_dpp v1, v3, v3 row_mirror row_mask:0xf bank_mask:0xf
	s_nop 1
	v_add_f32_dpp v2, v1, v1 row_bcast:15 row_mask:0xa bank_mask:0xf
	v_or3_b32 v4, v5, v0, s77
	v_ashrrev_i32_e32 v5, 31, v4
	v_lshl_add_u64 v[4:5], v[4:5], 1, s[12:13]
	global_store_short v[4:5], v6, off
	s_and_saveexec_b64 s[10:11], s[8:9]
	s_cbranch_execz .LBB0_464
	v_mov_b32_e32 v1, v2
	ds_add_f32 v18, v1 offset:36712

; DI bf16_t f2bf(float f) { return (bf16_t)(pk2(f, 0.f) & 0xffffu); }
; DI int fragoff(int row, int k, int KS) { return (((row >> 4) * KS + (k >> 5)) << 9) + (((((k >> 3) & 3) << 4) + (row & 15)) << 3) + (k & 7); }
; DI int crow32(int r, int half) { return (r & 3) + 8 * (r >> 2) + 4 * half; }
; DI void mlstm_pre(const Params& p, int ch, char* smem) {
;     ...
;     for (int r = 0; r < 16; ++r) {
;       const int i = ti * 32 + crow32(r, lane >> 5);
;       float pv = (i >= j) ? acc[r] * __expf(s_bc[i] + cj - s_mt[i]) : 0.f;
;       o_p[fragoff(i, j, 2)] = f2bf(pv);
;       pv += __shfl_xor(pv, 1);
;       pv += __shfl_xor(pv, 2);
;       pv += __shfl_xor(pv, 4);
;       pv += __shfl_xor(pv, 8);
;       pv += __shfl_xor(pv, 16);
;       if ((lane & 31) == 0) atomicAdd(&s_rs[i], pv);
;     }
.LBB0_466:
	s_or_b64 exec, exec, s[14:15]
	v_lshrrev_b32_e32 v1, 3, v1
	v_and_or_b32 v1, v1, s80, v16
	v_lshl_or_b32 v5, v1, 9, v21
	v_cvt_pk_bf16_f32 v6, v2, s0
	s_nop 1
	v_add_f32_dpp v3, v2, v2 quad_perm:[1,0,3,2] row_mask:0xf bank_mask:0xf
	s_nop 1
	v_add_f32_dpp v3, v3, v3 quad_perm:[2,3,0,1] row_mask:0xf bank_mask:0xf
	s_nop 1
	v_add_f32_dpp v3, v3, v3 row_half_mirror row_mask:0xf bank_mask:0xf
	s_nop 1
	v_add_f32_dpp v1, v3, v3 row_mirror row_mask:0xf bank_mask:0xf
	s_nop 1
	v_add_f32_dpp v2, v1, v1 row_bcast:15 row_mask:0xa bank_mask:0xf
	v_or3_b32 v4, v5, v0, s78
	v_ashrrev_i32_e32 v5, 31, v4
	v_lshl_add_u64 v[4:5], v[4:5], 1, s[12:13]
	global_store_short v[4:5], v6, off
	s_and_saveexec_b64 s[10:11], s[8:9]
	s_cbranch_execz .LBB0_468
	v_mov_b32_e32 v0, v2
	ds_add_f32 v18, v0 offset:36716
